# GEMM units: accumulator zeroing (128 v_mov per unit) removed; first K-loop iteration peeled, its first MFMA into each accumulator takes C = 0
# speedup vs baseline: 1.0079x; 1.0079x over previous
.LBB0_487:
	s_add_u32 s36, s36, 0x80
	s_addc_u32 s37, s37, 0
	s_add_u32 s38, s58, 0x100
	s_addc_u32 s39, s59, 0
	s_mov_b32 s46, 0
	s_add_i32 s58, s46, 2
	s_add_u32 s59, s36, 0x80
	s_addc_u32 s47, s37, 0
	s_add_i32 s96, 0, 0x10000
	s_cmp_eq_u32 s72, s46
	s_cselect_b32 s47, s55, s47
	s_cselect_b32 s46, s54, s59
	v_add_u32_e32 v146, s96, v149
	s_cselect_b32 vcc_hi, s57, s39
	s_cselect_b32 vcc_lo, s56, s38
	s_add_i32 s59, 0, 0x14000
	s_waitcnt lgkmcnt(0)
	ds_read_b128 v[142:145], v146
	ds_read_b128 v[158:161], v146 offset:1024
	ds_read_b128 v[166:169], v146 offset:2048
	ds_read_b128 v[170:173], v146 offset:3072
	v_add_u32_e32 v146, s59, v149
	ds_read_b128 v[174:177], v146
	ds_read_b128 v[178:181], v146 offset:1024
	ds_read_b128 v[182:185], v146 offset:2048
	ds_read_b128 v[186:189], v146 offset:3072
	v_lshl_add_u64 v[146:147], s[36:37], 0, v[138:139]
	s_add_i32 m0, s61, 0xc000
	ds_read_b128 v[190:193], v157
	ds_read_b128 v[194:197], v157 offset:1024
	ds_read_b128 v[198:201], v157 offset:2048
	ds_read_b128 v[202:205], v157 offset:3072
	ds_read_b128 v[230:233], v157 offset:4096
	ds_read_b128 v[234:237], v157 offset:5120
	ds_read_b128 v[238:241], v157 offset:6144
	ds_read_b128 v[242:245], v157 offset:7168
	global_load_lds_dwordx4 v[146:147], off
	v_lshl_add_u64 v[146:147], s[36:37], 0, v[140:141]
	s_add_i32 m0, s61, 0xe000
	s_nop 0
	global_load_lds_dwordx4 v[146:147], off
	s_waitcnt vmcnt(8)
	s_waitcnt lgkmcnt(0)
	s_barrier
	s_setprio 1
	s_waitcnt lgkmcnt(0)
	v_mfma_f32_16x16x32_bf16 v[124:127], v[142:145], v[190:193], 0
	v_mfma_f32_16x16x32_bf16 v[120:123], v[166:169], v[190:193], 0
	v_mfma_f32_16x16x32_bf16 v[108:111], v[142:145], v[198:201], 0
	v_mfma_f32_16x16x32_bf16 v[104:107], v[166:169], v[198:201], 0
	v_mfma_f32_16x16x32_bf16 v[92:95], v[142:145], v[230:233], 0
	v_mfma_f32_16x16x32_bf16 v[88:91], v[166:169], v[230:233], 0
	v_mfma_f32_16x16x32_bf16 v[76:79], v[142:145], v[238:241], 0
	v_mfma_f32_16x16x32_bf16 v[72:75], v[166:169], v[238:241], 0
	v_mfma_f32_16x16x32_bf16 v[124:127], v[158:161], v[194:197], v[124:127]
	v_mfma_f32_16x16x32_bf16 v[120:123], v[170:173], v[194:197], v[120:123]
	v_mfma_f32_16x16x32_bf16 v[108:111], v[158:161], v[202:205], v[108:111]
	v_mfma_f32_16x16x32_bf16 v[104:107], v[170:173], v[202:205], v[104:107]
	v_mfma_f32_16x16x32_bf16 v[92:95], v[158:161], v[234:237], v[92:95]
	v_mfma_f32_16x16x32_bf16 v[88:91], v[170:173], v[234:237], v[88:91]
	v_mfma_f32_16x16x32_bf16 v[76:79], v[158:161], v[242:245], v[76:79]
	v_mfma_f32_16x16x32_bf16 v[72:75], v[170:173], v[242:245], v[72:75]
	s_setprio 0
	s_setprio 1
	v_mfma_f32_16x16x32_bf16 v[116:119], v[174:177], v[190:193], 0
	v_mfma_f32_16x16x32_bf16 v[112:115], v[182:185], v[190:193], 0
	v_mfma_f32_16x16x32_bf16 v[100:103], v[174:177], v[198:201], 0
	v_mfma_f32_16x16x32_bf16 v[96:99], v[182:185], v[198:201], 0
	v_mfma_f32_16x16x32_bf16 v[84:87], v[174:177], v[230:233], 0
	v_mfma_f32_16x16x32_bf16 v[80:83], v[182:185], v[230:233], 0
	v_mfma_f32_16x16x32_bf16 v[68:71], v[174:177], v[238:241], 0
	v_mfma_f32_16x16x32_bf16 v[64:67], v[182:185], v[238:241], 0
	v_mfma_f32_16x16x32_bf16 v[116:119], v[178:181], v[194:197], v[116:119]
	v_mfma_f32_16x16x32_bf16 v[112:115], v[186:189], v[194:197], v[112:115]
	v_mfma_f32_16x16x32_bf16 v[100:103], v[178:181], v[202:205], v[100:103]
	v_mfma_f32_16x16x32_bf16 v[96:99], v[186:189], v[202:205], v[96:99]
	v_mfma_f32_16x16x32_bf16 v[84:87], v[178:181], v[234:237], v[84:87]
	v_mfma_f32_16x16x32_bf16 v[80:83], v[186:189], v[234:237], v[80:83]
	v_mfma_f32_16x16x32_bf16 v[68:71], v[178:181], v[242:245], v[68:71]
	v_mfma_f32_16x16x32_bf16 v[64:67], v[186:189], v[242:245], v[64:67]
	s_setprio 0
	s_barrier
	s_add_i32 s96, s96, s60
	v_lshl_add_u64 v[146:147], vcc, 0, v[130:131]
	s_mov_b32 m0, s96
	ds_read_b128 v[190:193], v157 offset:16384
	ds_read_b128 v[194:197], v157 offset:17408
	ds_read_b128 v[198:201], v157 offset:18432
	ds_read_b128 v[202:205], v157 offset:19456
	ds_read_b128 v[230:233], v157 offset:20480
	ds_read_b128 v[234:237], v157 offset:21504
	ds_read_b128 v[238:241], v157 offset:22528
	ds_read_b128 v[242:245], v157 offset:23552
	global_load_lds_dwordx4 v[146:147], off
	s_add_i32 m0, s96, 0x2000
	v_lshl_add_u64 v[206:207], vcc, 0, v[134:135]
	s_add_u32 vcc_lo, vcc_lo, s26
	s_addc_u32 vcc_hi, vcc_hi, 0
	s_add_i32 s59, s59, s60
	global_load_lds_dwordx4 v[206:207], off
	v_lshl_add_u64 v[246:247], vcc, 0, v[130:131]
	s_mov_b32 m0, s59
	v_lshl_add_u64 v[248:249], vcc, 0, v[134:135]
	global_load_lds_dwordx4 v[246:247], off
	s_add_i32 m0, s59, 0x2000
	v_lshl_add_u64 v[250:251], s[46:47], 0, v[128:129]
	global_load_lds_dwordx4 v[248:249], off
	s_mov_b32 m0, s61
	v_lshl_add_u64 v[252:253], s[46:47], 0, v[132:133]
	global_load_lds_dwordx4 v[250:251], off
	s_mov_b32 m0, s62
	s_nop 0
	global_load_lds_dwordx4 v[252:253], off
	s_waitcnt vmcnt(8)
	s_waitcnt lgkmcnt(0)
	s_barrier
	s_setprio 1
	s_waitcnt lgkmcnt(0)
	v_mfma_f32_16x16x32_bf16 v[60:63], v[142:145], v[190:193], 0
	v_mfma_f32_16x16x32_bf16 v[56:59], v[166:169], v[190:193], 0
	v_mfma_f32_16x16x32_bf16 v[44:47], v[142:145], v[198:201], 0
	v_mfma_f32_16x16x32_bf16 v[40:43], v[166:169], v[198:201], 0
	v_mfma_f32_16x16x32_bf16 v[28:31], v[142:145], v[230:233], 0
	v_mfma_f32_16x16x32_bf16 v[24:27], v[166:169], v[230:233], 0
	v_mfma_f32_16x16x32_bf16 v[12:15], v[142:145], v[238:241], 0
	v_mfma_f32_16x16x32_bf16 v[8:11], v[166:169], v[238:241], 0
	v_mfma_f32_16x16x32_bf16 v[60:63], v[158:161], v[194:197], v[60:63]
	v_mfma_f32_16x16x32_bf16 v[56:59], v[170:173], v[194:197], v[56:59]
	v_mfma_f32_16x16x32_bf16 v[44:47], v[158:161], v[202:205], v[44:47]
	v_mfma_f32_16x16x32_bf16 v[40:43], v[170:173], v[202:205], v[40:43]
	v_mfma_f32_16x16x32_bf16 v[28:31], v[158:161], v[234:237], v[28:31]
	v_mfma_f32_16x16x32_bf16 v[24:27], v[170:173], v[234:237], v[24:27]
	v_mfma_f32_16x16x32_bf16 v[12:15], v[158:161], v[242:245], v[12:15]
	v_mfma_f32_16x16x32_bf16 v[8:11], v[170:173], v[242:245], v[8:11]
	s_setprio 0
	s_setprio 1
	v_mfma_f32_16x16x32_bf16 v[52:55], v[174:177], v[190:193], 0
	v_mfma_f32_16x16x32_bf16 v[48:51], v[182:185], v[190:193], 0
	v_mfma_f32_16x16x32_bf16 v[36:39], v[174:177], v[198:201], 0
	v_mfma_f32_16x16x32_bf16 v[32:35], v[182:185], v[198:201], 0
	v_mfma_f32_16x16x32_bf16 v[20:23], v[174:177], v[230:233], 0
	v_mfma_f32_16x16x32_bf16 v[16:19], v[182:185], v[230:233], 0
	v_mfma_f32_16x16x32_bf16 v[4:7], v[174:177], v[238:241], 0
	v_mfma_f32_16x16x32_bf16 v[0:3], v[182:185], v[238:241], 0
	v_mfma_f32_16x16x32_bf16 v[52:55], v[178:181], v[194:197], v[52:55]
	v_mfma_f32_16x16x32_bf16 v[48:51], v[186:189], v[194:197], v[48:51]
	v_mfma_f32_16x16x32_bf16 v[36:39], v[178:181], v[202:205], v[36:39]
	v_mfma_f32_16x16x32_bf16 v[32:35], v[186:189], v[202:205], v[32:35]
	v_mfma_f32_16x16x32_bf16 v[20:23], v[178:181], v[234:237], v[20:23]
	v_mfma_f32_16x16x32_bf16 v[16:19], v[186:189], v[234:237], v[16:19]
	v_mfma_f32_16x16x32_bf16 v[4:7], v[178:181], v[242:245], v[4:7]
	v_mfma_f32_16x16x32_bf16 v[0:3], v[186:189], v[242:245], v[0:3]
	s_setprio 0
	s_barrier
	s_add_i32 s59, 0, 0x18000
	v_add_u32_e32 v162, s59, v149
	s_add_i32 s96, 0, 0x1c000
	ds_read_b128 v[142:145], v162
	ds_read_b128 v[158:161], v162 offset:1024
	ds_read_b128 v[166:169], v162 offset:2048
	ds_read_b128 v[170:173], v162 offset:3072
	v_add_u32_e32 v162, s96, v149
	ds_read_b128 v[174:177], v162
	ds_read_b128 v[178:181], v162 offset:1024
	ds_read_b128 v[182:185], v162 offset:2048
	ds_read_b128 v[186:189], v162 offset:3072
	s_add_u32 s46, s46, s26
	s_addc_u32 s47, s47, 0
	s_mov_b32 m0, s63
	v_lshl_add_u64 v[214:215], s[46:47], 0, v[128:129]
	ds_read_b128 v[190:193], v157 offset:32768
	ds_read_b128 v[194:197], v157 offset:33792
	ds_read_b128 v[198:201], v157 offset:34816
	ds_read_b128 v[202:205], v157 offset:35840
	ds_read_b128 v[230:233], v157 offset:36864
	ds_read_b128 v[234:237], v157 offset:37888
	ds_read_b128 v[238:241], v157 offset:38912
	ds_read_b128 v[242:245], v157 offset:39936
	global_load_lds_dwordx4 v[214:215], off
	v_lshl_add_u64 v[214:215], s[46:47], 0, v[132:133]
	s_mov_b32 m0, s64
	s_nop 0
	global_load_lds_dwordx4 v[214:215], off
	s_waitcnt vmcnt(8)
	s_waitcnt lgkmcnt(0)
	s_barrier
	s_setprio 1
	s_waitcnt lgkmcnt(0)
	v_mfma_f32_16x16x32_bf16 v[124:127], v[142:145], v[190:193], v[124:127]
	v_mfma_f32_16x16x32_bf16 v[120:123], v[166:169], v[190:193], v[120:123]
	v_mfma_f32_16x16x32_bf16 v[108:111], v[142:145], v[198:201], v[108:111]
	v_mfma_f32_16x16x32_bf16 v[104:107], v[166:169], v[198:201], v[104:107]
	v_mfma_f32_16x16x32_bf16 v[92:95], v[142:145], v[230:233], v[92:95]
	v_mfma_f32_16x16x32_bf16 v[88:91], v[166:169], v[230:233], v[88:91]
	v_mfma_f32_16x16x32_bf16 v[76:79], v[142:145], v[238:241], v[76:79]
	v_mfma_f32_16x16x32_bf16 v[72:75], v[166:169], v[238:241], v[72:75]
	v_mfma_f32_16x16x32_bf16 v[124:127], v[158:161], v[194:197], v[124:127]
	v_mfma_f32_16x16x32_bf16 v[120:123], v[170:173], v[194:197], v[120:123]
	v_mfma_f32_16x16x32_bf16 v[108:111], v[158:161], v[202:205], v[108:111]
	v_mfma_f32_16x16x32_bf16 v[104:107], v[170:173], v[202:205], v[104:107]
	v_mfma_f32_16x16x32_bf16 v[92:95], v[158:161], v[234:237], v[92:95]
	v_mfma_f32_16x16x32_bf16 v[88:91], v[170:173], v[234:237], v[88:91]
	v_mfma_f32_16x16x32_bf16 v[76:79], v[158:161], v[242:245], v[76:79]
	v_mfma_f32_16x16x32_bf16 v[72:75], v[170:173], v[242:245], v[72:75]
	s_setprio 0
	s_setprio 1
	v_mfma_f32_16x16x32_bf16 v[116:119], v[174:177], v[190:193], v[116:119]
	v_mfma_f32_16x16x32_bf16 v[112:115], v[182:185], v[190:193], v[112:115]
	v_mfma_f32_16x16x32_bf16 v[100:103], v[174:177], v[198:201], v[100:103]
	v_mfma_f32_16x16x32_bf16 v[96:99], v[182:185], v[198:201], v[96:99]
	v_mfma_f32_16x16x32_bf16 v[84:87], v[174:177], v[230:233], v[84:87]
	v_mfma_f32_16x16x32_bf16 v[80:83], v[182:185], v[230:233], v[80:83]
	v_mfma_f32_16x16x32_bf16 v[68:71], v[174:177], v[238:241], v[68:71]
	v_mfma_f32_16x16x32_bf16 v[64:67], v[182:185], v[238:241], v[64:67]
	v_mfma_f32_16x16x32_bf16 v[116:119], v[178:181], v[194:197], v[116:119]
	v_mfma_f32_16x16x32_bf16 v[112:115], v[186:189], v[194:197], v[112:115]
	v_mfma_f32_16x16x32_bf16 v[100:103], v[178:181], v[202:205], v[100:103]
	v_mfma_f32_16x16x32_bf16 v[96:99], v[186:189], v[202:205], v[96:99]
	v_mfma_f32_16x16x32_bf16 v[84:87], v[178:181], v[234:237], v[84:87]
	v_mfma_f32_16x16x32_bf16 v[80:83], v[186:189], v[234:237], v[80:83]
	v_mfma_f32_16x16x32_bf16 v[68:71], v[178:181], v[242:245], v[68:71]
	v_mfma_f32_16x16x32_bf16 v[64:67], v[186:189], v[242:245], v[64:67]
	s_setprio 0
	s_barrier
	s_add_i32 s46, s59, s60
	v_lshl_add_u64 v[146:147], v[146:147], 0, s[8:9]
	s_mov_b32 m0, s46
	ds_read_b128 v[190:193], v157 offset:49152
	ds_read_b128 v[194:197], v157 offset:50176
	ds_read_b128 v[198:201], v157 offset:51200
	ds_read_b128 v[202:205], v157 offset:52224
	ds_read_b128 v[230:233], v157 offset:53248
	ds_read_b128 v[234:237], v157 offset:54272
	ds_read_b128 v[238:241], v157 offset:55296
	ds_read_b128 v[242:245], v157 offset:56320
	global_load_lds_dwordx4 v[146:147], off
	v_lshl_add_u64 v[146:147], v[206:207], 0, s[8:9]
	s_add_i32 m0, s46, 0x2000
	s_add_i32 s46, s96, s60
	global_load_lds_dwordx4 v[146:147], off
	v_lshl_add_u64 v[146:147], v[246:247], 0, s[8:9]
	s_mov_b32 m0, s46
	s_nop 0
	global_load_lds_dwordx4 v[146:147], off
	v_lshl_add_u64 v[146:147], v[248:249], 0, s[8:9]
	s_add_i32 m0, s46, 0x2000
	s_nop 0
	global_load_lds_dwordx4 v[146:147], off
	v_lshl_add_u64 v[146:147], v[250:251], 0, s[8:9]
	s_mov_b32 m0, s70
	s_nop 0
	global_load_lds_dwordx4 v[146:147], off
	v_lshl_add_u64 v[146:147], v[252:253], 0, s[8:9]
	s_mov_b32 m0, s71
	s_nop 0
	global_load_lds_dwordx4 v[146:147], off
	s_waitcnt vmcnt(8)
	s_waitcnt lgkmcnt(0)
	s_barrier
	s_setprio 1
	s_waitcnt lgkmcnt(0)
	v_mfma_f32_16x16x32_bf16 v[60:63], v[142:145], v[190:193], v[60:63]
	v_mfma_f32_16x16x32_bf16 v[56:59], v[166:169], v[190:193], v[56:59]
	v_mfma_f32_16x16x32_bf16 v[44:47], v[142:145], v[198:201], v[44:47]
	v_mfma_f32_16x16x32_bf16 v[40:43], v[166:169], v[198:201], v[40:43]
	v_mfma_f32_16x16x32_bf16 v[28:31], v[142:145], v[230:233], v[28:31]
	v_mfma_f32_16x16x32_bf16 v[24:27], v[166:169], v[230:233], v[24:27]
	v_mfma_f32_16x16x32_bf16 v[12:15], v[142:145], v[238:241], v[12:15]
	v_mfma_f32_16x16x32_bf16 v[8:11], v[166:169], v[238:241], v[8:11]
	v_mfma_f32_16x16x32_bf16 v[60:63], v[158:161], v[194:197], v[60:63]
	v_mfma_f32_16x16x32_bf16 v[56:59], v[170:173], v[194:197], v[56:59]
	v_mfma_f32_16x16x32_bf16 v[44:47], v[158:161], v[202:205], v[44:47]
	v_mfma_f32_16x16x32_bf16 v[40:43], v[170:173], v[202:205], v[40:43]
	v_mfma_f32_16x16x32_bf16 v[28:31], v[158:161], v[234:237], v[28:31]
	v_mfma_f32_16x16x32_bf16 v[24:27], v[170:173], v[234:237], v[24:27]
	v_mfma_f32_16x16x32_bf16 v[12:15], v[158:161], v[242:245], v[12:15]
	v_mfma_f32_16x16x32_bf16 v[8:11], v[170:173], v[242:245], v[8:11]
	s_setprio 0
	s_setprio 1
	v_mfma_f32_16x16x32_bf16 v[52:55], v[174:177], v[190:193], v[52:55]
	v_mfma_f32_16x16x32_bf16 v[48:51], v[182:185], v[190:193], v[48:51]
	v_mfma_f32_16x16x32_bf16 v[36:39], v[174:177], v[198:201], v[36:39]
	v_mfma_f32_16x16x32_bf16 v[32:35], v[182:185], v[198:201], v[32:35]
	v_mfma_f32_16x16x32_bf16 v[20:23], v[174:177], v[230:233], v[20:23]
	v_mfma_f32_16x16x32_bf16 v[16:19], v[182:185], v[230:233], v[16:19]
	v_mfma_f32_16x16x32_bf16 v[4:7], v[174:177], v[238:241], v[4:7]
	v_mfma_f32_16x16x32_bf16 v[0:3], v[182:185], v[238:241], v[0:3]
	v_mfma_f32_16x16x32_bf16 v[52:55], v[178:181], v[194:197], v[52:55]
	v_mfma_f32_16x16x32_bf16 v[48:51], v[186:189], v[194:197], v[48:51]
	v_mfma_f32_16x16x32_bf16 v[36:39], v[178:181], v[202:205], v[36:39]
	v_mfma_f32_16x16x32_bf16 v[32:35], v[186:189], v[202:205], v[32:35]
	v_mfma_f32_16x16x32_bf16 v[20:23], v[178:181], v[234:237], v[20:23]
	v_mfma_f32_16x16x32_bf16 v[16:19], v[186:189], v[234:237], v[16:19]
	v_mfma_f32_16x16x32_bf16 v[4:7], v[178:181], v[242:245], v[4:7]
	v_mfma_f32_16x16x32_bf16 v[0:3], v[186:189], v[242:245], v[0:3]
	s_setprio 0
	s_barrier
	s_add_u32 s36, s36, 0x100
	s_addc_u32 s37, s37, 0
	s_add_u32 s38, s38, 0x100
	s_addc_u32 s39, s39, 0
	s_cmp_ge_u32 s58, s66
	s_mov_b32 s46, s58
